# also hoist the max select and the 16 in-place softmax fmamk of the next tile into the last PV slots before the tile barrier
# baseline (speedup 1.0000x reference)
.LBB0_1096:
	ds_read_b128 v[64:67], v194 offset:49152
	ds_read_b128 v[68:71], v195 offset:57344
	ds_read_b128 v[214:217], v196 offset:49152
	ds_read_b128 v[224:227], v197 offset:57344
	v_add_f32_e32 v160, 0, v175
	v_add_f32_e32 v160, v223, v160
	s_waitcnt lgkmcnt(3)
	v_mfma_f32_32x32x16_bf16 v[80:95], v[64:67], v[100:103], 0
	v_add_f32_e32 v160, v161, v160
	v_add_f32_e32 v160, v220, v160
	v_add_f32_e32 v160, v162, v160
	v_add_f32_e32 v160, v174, v160
	v_add_f32_e32 v160, v163, v160
	v_add_f32_e32 v160, v173, v160
	v_add_f32_e32 v160, v164, v160
	s_waitcnt lgkmcnt(2)
	v_mfma_f32_32x32x16_bf16 v[64:79], v[68:71], v[100:103], 0
	v_add_f32_e32 v160, v172, v160
	v_add_f32_e32 v160, v165, v160
	v_add_f32_e32 v160, v171, v160
	v_exp_f32_e32 v156, v156
	v_add_f32_e32 v160, v166, v160
	v_exp_f32_e32 v157, v157
	v_add_f32_e32 v160, v170, v160
	s_waitcnt lgkmcnt(1)
	v_mfma_f32_32x32x16_bf16 v[80:95], v[214:217], v[108:111], v[80:95]
	v_exp_f32_e32 v154, v154
	v_add_f32_e32 v160, v167, v160
	v_exp_f32_e32 v155, v155
	v_add_f32_e32 v160, v169, v160
	v_exp_f32_e32 v148, v148
	v_add_f32_e32 v160, v156, v160
	v_exp_f32_e32 v149, v149
	s_waitcnt lgkmcnt(0)
	v_mfma_f32_32x32x16_bf16 v[64:79], v[224:227], v[108:111], v[64:79]
	ds_read_b128 v[214:217], v198 offset:49152
	ds_read_b128 v[224:227], v200 offset:57344
	v_add_f32_e32 v160, v157, v160
	v_exp_f32_e32 v146, v146
	v_add_f32_e32 v160, v154, v160
	v_exp_f32_e32 v147, v147
	v_add_f32_e32 v160, v155, v160
	v_exp_f32_e32 v144, v144
	s_waitcnt lgkmcnt(1)
	v_mfma_f32_32x32x16_bf16 v[80:95], v[214:217], v[96:99], v[80:95]
	v_add_f32_e32 v160, v148, v160
	v_exp_f32_e32 v145, v145
	v_add_f32_e32 v160, v149, v160
	v_exp_f32_e32 v158, v158
	v_add_f32_e32 v160, v146, v160
	v_exp_f32_e32 v159, v159
	v_add_f32_e32 v160, v147, v160
	s_waitcnt lgkmcnt(0)
	v_mfma_f32_32x32x16_bf16 v[64:79], v[224:227], v[96:99], v[64:79]
	ds_read_b128 v[214:217], v199 offset:49152
	ds_read_b128 v[224:227], v201 offset:57344
	v_exp_f32_e32 v152, v152
	v_add_f32_e32 v160, v144, v160
	v_exp_f32_e32 v153, v153
	v_add_f32_e32 v160, v145, v160
	v_exp_f32_e32 v150, v150
	v_add_f32_e32 v160, v158, v160
	s_waitcnt lgkmcnt(1)
	v_mfma_f32_32x32x16_bf16 v[80:95], v[214:217], v[104:107], v[80:95]
	v_exp_f32_e32 v151, v151
	v_add_f32_e32 v160, v159, v160
	v_add_f32_e32 v160, v152, v160
	v_add_f32_e32 v160, v153, v160
	v_add_f32_e32 v160, v150, v160
	v_add_f32_e32 v211, v151, v160
	v_mov_b32_e32 v218, v211
	s_waitcnt lgkmcnt(0)
	v_mfma_f32_32x32x16_bf16 v[64:79], v[224:227], v[104:107], v[64:79]
	ds_read_b128 v[214:217], v202 offset:49152
	ds_read_b128 v[224:227], v203 offset:57344
	v_permlane32_swap_b32_e32 v211, v218
	s_waitcnt lgkmcnt(1)
	v_mfma_f32_32x32x16_bf16 v[80:95], v[214:217], v[116:119], v[80:95]
	s_waitcnt lgkmcnt(0)
	v_mfma_f32_32x32x16_bf16 v[64:79], v[224:227], v[116:119], v[64:79]
	ds_read_b128 v[214:217], v204 offset:49152
	ds_read_b128 v[224:227], v205 offset:57344
	s_waitcnt lgkmcnt(1)
	v_mfma_f32_32x32x16_bf16 v[80:95], v[214:217], v[124:127], v[80:95]
	s_waitcnt lgkmcnt(0)
	v_mfma_f32_32x32x16_bf16 v[64:79], v[224:227], v[124:127], v[64:79]
	ds_read_b128 v[214:217], v206 offset:49152
	ds_read_b128 v[224:227], v208 offset:57344
	s_waitcnt lgkmcnt(1)
	v_mfma_f32_32x32x16_bf16 v[80:95], v[214:217], v[112:115], v[80:95]
	s_waitcnt lgkmcnt(0)
	v_mfma_f32_32x32x16_bf16 v[64:79], v[224:227], v[112:115], v[64:79]
	ds_read_b128 v[214:217], v207 offset:49152
	ds_read_b128 v[224:227], v209 offset:57344
	v_cvt_pk_bf16_f32 v160, v175, v223
	v_cvt_pk_bf16_f32 v161, v161, v220
	v_cvt_pk_bf16_f32 v162, v162, v174
	v_cvt_pk_bf16_f32 v163, v163, v173
	v_cvt_pk_bf16_f32 v164, v164, v172
	v_cvt_pk_bf16_f32 v165, v165, v171
	s_waitcnt lgkmcnt(1)
	v_mfma_f32_32x32x16_bf16 v[80:95], v[214:217], v[120:123], v[80:95]
	v_permlane32_swap_b32_e32 v160, v162
	v_cvt_pk_bf16_f32 v166, v166, v170
	v_cvt_pk_bf16_f32 v167, v167, v169
	v_cvt_pk_bf16_f32 v170, v156, v157
	v_cvt_pk_bf16_f32 v171, v154, v155
	v_cvt_pk_bf16_f32 v172, v148, v149
	s_waitcnt lgkmcnt(0)
	v_mfma_f32_32x32x16_bf16 v[64:79], v[224:227], v[120:123], v[64:79]
	v_cvt_pk_bf16_f32 v173, v146, v147
	v_cvt_pk_bf16_f32 v214, v144, v145
	v_cvt_pk_bf16_f32 v215, v158, v159
	v_cvt_pk_bf16_f32 v216, v152, v153
	v_cvt_pk_bf16_f32 v217, v150, v151
	v_permlane32_swap_b32_e32 v161, v163
	v_permlane32_swap_b32_e32 v164, v166
	v_permlane32_swap_b32_e32 v165, v167
	v_permlane32_swap_b32_e32 v170, v172
	v_permlane32_swap_b32_e32 v171, v173
	v_permlane32_swap_b32_e32 v214, v216
	v_permlane32_swap_b32_e32 v215, v217
	v_lshl_add_u64 v[144:145], v[180:181], 0, s[8:9]
	s_mov_b32 s2, 0x322f0000
	v_add_co_u32_e32 v146, vcc, s2, v144
	s_mov_b32 s2, 0x32318000
	s_nop 0
	v_addc_co_u32_e32 v147, vcc, 0, v145, vcc
	v_add_co_u32_e32 v148, vcc, s2, v144
	v_lshl_add_u64 v[152:153], v[178:179], 0, s[8:9]
	s_nop 0
	v_addc_co_u32_e32 v149, vcc, 0, v145, vcc
	s_mov_b32 s2, 0x41018000
	v_add_co_u32_e32 v154, vcc, s2, v152
	s_mov_b32 s2, 0x4101c000
	s_nop 0
	v_addc_co_u32_e32 v155, vcc, 0, v153, vcc
	v_add_co_u32_e32 v156, vcc, s2, v152
	global_load_dwordx4 v[144:147], v[146:147], off offset:2560
	s_nop 0
	global_load_dwordx4 v[148:151], v[148:149], off offset:2560
	v_addc_co_u32_e32 v157, vcc, 0, v153, vcc
	global_load_dwordx4 v[152:155], v[154:155], off
	s_nop 0
	global_load_dwordx4 v[156:159], v[156:157], off
	ds_read_b64_tr_b16 v[220:221], v189 offset:0
	ds_read_b64_tr_b16 v[222:223], v189 offset:0x800
	ds_read_b64_tr_b16 v[224:225], v189 offset:0x200
	ds_read_b64_tr_b16 v[226:227], v189 offset:0xa00
	ds_read_b64_tr_b16 v[230:231], v189 offset:0x400
	ds_read_b64_tr_b16 v[232:233], v189 offset:0xc00
	ds_read_b64_tr_b16 v[238:239], v189 offset:0x600
	ds_read_b64_tr_b16 v[240:241], v189 offset:0xe00
	s_waitcnt lgkmcnt(6)
	s_nop 0
	v_mfma_f32_32x32x16_bf16 v[0:15], v[160:163], v[220:223], v[0:15]
	ds_read_b64_tr_b16 v[220:221], v189 offset:0x1000
	ds_read_b64_tr_b16 v[222:223], v189 offset:0x1800
	s_waitcnt lgkmcnt(6)
	v_mfma_f32_32x32x16_bf16 v[48:63], v[160:163], v[224:227], v[48:63]
	ds_read_b64_tr_b16 v[224:225], v189 offset:0x1200
	ds_read_b64_tr_b16 v[226:227], v189 offset:0x1a00
	s_waitcnt lgkmcnt(6)
	v_mfma_f32_32x32x16_bf16 v[32:47], v[160:163], v[230:233], v[32:47]
	ds_read_b64_tr_b16 v[230:231], v189 offset:0x1400
	ds_read_b64_tr_b16 v[232:233], v189 offset:0x1c00
	s_waitcnt lgkmcnt(6)
	v_mfma_f32_32x32x16_bf16 v[16:31], v[160:163], v[238:241], v[16:31]
	ds_read_b64_tr_b16 v[238:239], v189 offset:0x1600
	ds_read_b64_tr_b16 v[240:241], v189 offset:0x1e00
	s_waitcnt lgkmcnt(6)
	v_mfma_f32_32x32x16_bf16 v[0:15], v[164:167], v[220:223], v[0:15]
	ds_read_b64_tr_b16 v[220:221], v189 offset:0x2000
	ds_read_b64_tr_b16 v[222:223], v189 offset:0x2800
	v_max_f32_e32 v160, v81, v81
	v_max_f32_e32 v161, v80, v80
	v_max_f32_e32 v160, v161, v160
	v_max3_f32 v160, v160, v82, v83
	v_max3_f32 v160, v160, v84, v85
	v_max3_f32 v160, v160, v86, v87
	v_max3_f32 v160, v160, v88, v89
	v_max3_f32 v160, v160, v90, v91
	s_waitcnt lgkmcnt(6)
	v_mfma_f32_32x32x16_bf16 v[48:63], v[164:167], v[224:227], v[48:63]
	ds_read_b64_tr_b16 v[224:225], v189 offset:0x2200
	ds_read_b64_tr_b16 v[226:227], v189 offset:0x2a00
	s_waitcnt lgkmcnt(6)
	v_mfma_f32_32x32x16_bf16 v[32:47], v[164:167], v[230:233], v[32:47]
	ds_read_b64_tr_b16 v[230:231], v189 offset:0x2400
	ds_read_b64_tr_b16 v[232:233], v189 offset:0x2c00
	v_max3_f32 v160, v160, v92, v93
	v_max3_f32 v160, v160, v94, v95
	v_max3_f32 v160, v160, v64, v65
	v_max3_f32 v160, v160, v66, v67
	v_max3_f32 v160, v160, v68, v69
	v_max3_f32 v160, v160, v70, v71
	v_max3_f32 v160, v160, v72, v73
	v_max3_f32 v160, v160, v74, v75
	s_waitcnt lgkmcnt(6)
	v_mfma_f32_32x32x16_bf16 v[16:31], v[164:167], v[238:241], v[16:31]
	ds_read_b64_tr_b16 v[238:239], v189 offset:0x2600
	ds_read_b64_tr_b16 v[240:241], v189 offset:0x2e00
	s_waitcnt lgkmcnt(6)
	v_mfma_f32_32x32x16_bf16 v[0:15], v[170:173], v[220:223], v[0:15]
	ds_read_b64_tr_b16 v[220:221], v189 offset:0x3000
	ds_read_b64_tr_b16 v[222:223], v189 offset:0x3800
	v_max3_f32 v160, v160, v76, v77
	v_max3_f32 v160, v160, v78, v79
	v_mov_b32_e32 v161, v160
	s_nop 1
	v_permlane32_swap_b32_e32 v160, v161
	v_max_f32_e32 v161, v161, v161
	v_max_f32_e32 v160, v160, v160
	v_max_f32_e32 v160, v160, v161
	s_waitcnt lgkmcnt(6)
	v_mfma_f32_32x32x16_bf16 v[48:63], v[170:173], v[224:227], v[48:63]
	ds_read_b64_tr_b16 v[224:225], v189 offset:0x3200
	ds_read_b64_tr_b16 v[226:227], v189 offset:0x3a00
	s_waitcnt lgkmcnt(6)
	v_mfma_f32_32x32x16_bf16 v[32:47], v[170:173], v[230:233], v[32:47]
	ds_read_b64_tr_b16 v[230:231], v189 offset:0x3400
	ds_read_b64_tr_b16 v[232:233], v189 offset:0x3c00
	v_sub_f32_e32 v161, v160, v168
	v_cmp_ge_f32_e32 vcc, s90, v161
	v_max_f32_e32 v161, v168, v168
	v_max_f32_e32 v160, v161, v160
	v_sub_f32_e32 v161, v168, v160
	v_mul_f32_e32 v161, 0x3e0293ee, v161
	v_exp_f32_e32 v161, v161
	s_cmp_eq_u64 vcc, exec
	s_cselect_b64 s[38:39], -1, 0
	s_waitcnt lgkmcnt(6)
	v_mfma_f32_32x32x16_bf16 v[16:31], v[170:173], v[238:241], v[16:31]
	ds_read_b64_tr_b16 v[238:239], v189 offset:0x3600
	ds_read_b64_tr_b16 v[240:241], v189 offset:0x3e00
	v_cndmask_b32_e64 v162, v160, v168, s[38:39]
	v_mul_f32_e32 v163, 0xbe0293ee, v162
	v_fmamk_f32 v80, v80, 0x3e0293ee, v163
	v_fmamk_f32 v81, v81, 0x3e0293ee, v163
	v_fmamk_f32 v82, v82, 0x3e0293ee, v163
	v_fmamk_f32 v83, v83, 0x3e0293ee, v163
	v_fmamk_f32 v84, v84, 0x3e0293ee, v163
	v_fmamk_f32 v85, v85, 0x3e0293ee, v163
	v_fmamk_f32 v86, v86, 0x3e0293ee, v163
	v_fmamk_f32 v87, v87, 0x3e0293ee, v163
	s_waitcnt lgkmcnt(6)
	v_mfma_f32_32x32x16_bf16 v[0:15], v[214:217], v[220:223], v[0:15]
	v_fmamk_f32 v88, v88, 0x3e0293ee, v163
	v_fmamk_f32 v89, v89, 0x3e0293ee, v163
	v_fmamk_f32 v90, v90, 0x3e0293ee, v163
	v_fmamk_f32 v91, v91, 0x3e0293ee, v163
	v_fmamk_f32 v92, v92, 0x3e0293ee, v163
	v_fmamk_f32 v93, v93, 0x3e0293ee, v163
	v_fmamk_f32 v94, v94, 0x3e0293ee, v163
	v_fmamk_f32 v95, v95, 0x3e0293ee, v163
	s_waitcnt lgkmcnt(0)
	s_barrier
	v_mfma_f32_32x32x16_bf16 v[48:63], v[214:217], v[224:227], v[48:63]
	s_waitcnt vmcnt(4)
	v_cndmask_b32_e64 v219, v161, 1.0, s[38:39]
	v_cmp_gt_f32_e32 vcc, 1.0, v219
	s_waitcnt vmcnt(7)
	ds_write_b128 v190, v[128:131]
	s_waitcnt vmcnt(6)
	ds_write_b128 v191, v[132:135]
	v_mfma_f32_32x32x16_bf16 v[32:47], v[214:217], v[230:233], v[32:47]
	s_waitcnt vmcnt(5)
	ds_write_b128 v192, v[136:139] offset:32768
	s_waitcnt vmcnt(4)
	ds_write_b128 v193, v[140:143] offset:32768
	v_mfma_f32_32x32x16_bf16 v[16:31], v[214:217], v[238:241], v[16:31]
	s_cbranch_vccz .LBB0_1100
	s_and_saveexec_b64 s[2:3], s[36:37]
	ds_write_b32 v186, v219 offset:128
	s_or_b64 exec, exec, s[2:3]
	s_waitcnt lgkmcnt(0)
	v_add_u32_e32 v161, s27, v185
	ds_read_b128 v[162:165], v161 offset:224
	ds_read_b128 v[170:173], v161 offset:192
	ds_read_b128 v[214:217], v161 offset:160
	ds_read_b128 v[220:223], v161 offset:128
	s_waitcnt lgkmcnt(3)
	v_pk_mul_f32 v[12:13], v[12:13], v[162:163]
	s_waitcnt lgkmcnt(2)
	v_pk_mul_f32 v[8:9], v[8:9], v[170:171]
	s_waitcnt lgkmcnt(1)
	v_pk_mul_f32 v[4:5], v[4:5], v[214:215]
	v_pk_mul_f32 v[14:15], v[14:15], v[164:165]
	v_pk_mul_f32 v[10:11], v[10:11], v[172:173]
	v_pk_mul_f32 v[6:7], v[6:7], v[216:217]
	s_waitcnt lgkmcnt(0)
	v_pk_mul_f32 v[2:3], v[2:3], v[222:223]
	v_pk_mul_f32 v[0:1], v[0:1], v[220:221]
	v_pk_mul_f32 v[60:61], v[60:61], v[162:163]
	v_pk_mul_f32 v[56:57], v[56:57], v[170:171]
	v_pk_mul_f32 v[52:53], v[52:53], v[214:215]
	v_pk_mul_f32 v[62:63], v[62:63], v[164:165]
	v_pk_mul_f32 v[58:59], v[58:59], v[172:173]
	v_pk_mul_f32 v[54:55], v[54:55], v[216:217]
	v_pk_mul_f32 v[50:51], v[50:51], v[222:223]
	v_pk_mul_f32 v[48:49], v[48:49], v[220:221]
	v_pk_mul_f32 v[44:45], v[44:45], v[162:163]
	v_pk_mul_f32 v[40:41], v[40:41], v[170:171]
	v_pk_mul_f32 v[36:37], v[36:37], v[214:215]
	v_pk_mul_f32 v[46:47], v[46:47], v[164:165]
	v_pk_mul_f32 v[42:43], v[42:43], v[172:173]
	v_pk_mul_f32 v[38:39], v[38:39], v[216:217]
	v_pk_mul_f32 v[34:35], v[34:35], v[222:223]
	v_pk_mul_f32 v[32:33], v[32:33], v[220:221]
	v_pk_mul_f32 v[28:29], v[28:29], v[162:163]
	v_pk_mul_f32 v[24:25], v[24:25], v[170:171]
	v_pk_mul_f32 v[20:21], v[20:21], v[214:215]
	v_pk_mul_f32 v[30:31], v[30:31], v[164:165]
	v_pk_mul_f32 v[26:27], v[26:27], v[172:173]
	v_pk_mul_f32 v[22:23], v[22:23], v[216:217]
	v_pk_mul_f32 v[18:19], v[18:19], v[222:223]
	v_pk_mul_f32 v[16:17], v[16:17], v[220:221]
.LBB0_1100:
	v_cndmask_b32_e64 v220, v160, v168, s[38:39]
	v_mul_f32_e32 v221, 0xbe0293ee, v220
	v_exp_f32_e32 v160, v80
	v_exp_f32_e32 v175, v81
	v_exp_f32_e32 v161, v82
	v_exp_f32_e32 v174, v83
	v_exp_f32_e32 v162, v84
	v_exp_f32_e32 v173, v85
	v_exp_f32_e32 v163, v86
	v_exp_f32_e32 v172, v87
	v_exp_f32_e32 v164, v88
	v_exp_f32_e32 v171, v89
	v_exp_f32_e32 v165, v90
	v_exp_f32_e32 v170, v91
	v_exp_f32_e32 v166, v92
	v_exp_f32_e32 v169, v93
	v_exp_f32_e32 v167, v94
	v_exp_f32_e32 v168, v95
	v_fmamk_f32 v240, v64, 0x3e0293ee, v221
	v_fmamk_f32 v241, v65, 0x3e0293ee, v221
	v_fmamk_f32 v242, v66, 0x3e0293ee, v221
	v_fmamk_f32 v243, v67, 0x3e0293ee, v221
	v_fmamk_f32 v244, v68, 0x3e0293ee, v221
	v_fmamk_f32 v223, v69, 0x3e0293ee, v221
	v_fmamk_f32 v224, v70, 0x3e0293ee, v221
	v_fmamk_f32 v225, v71, 0x3e0293ee, v221
	v_fmamk_f32 v226, v72, 0x3e0293ee, v221
	v_fmamk_f32 v227, v73, 0x3e0293ee, v221
	v_fmamk_f32 v238, v74, 0x3e0293ee, v221
	v_fmamk_f32 v239, v75, 0x3e0293ee, v221
	v_fmamk_f32 v222, v76, 0x3e0293ee, v221
	v_fmamk_f32 v245, v77, 0x3e0293ee, v221
	v_fmamk_f32 v246, v78, 0x3e0293ee, v221
	v_fmac_f32_e32 v221, 0x3e0293ee, v79
	s_waitcnt lgkmcnt(0)
	s_barrier
	ds_read_b128 v[64:67], v194 offset:32768
	ds_read_b128 v[68:71], v195 offset:40960
	ds_read_b128 v[214:217], v196 offset:32768
	ds_read_b128 v[230:233], v197 offset:40960
	v_exp_f32_e32 v223, v223
	v_exp_f32_e32 v224, v224
	s_waitcnt lgkmcnt(3)
	v_mfma_f32_32x32x16_bf16 v[80:95], v[64:67], v[100:103], 0
	v_exp_f32_e32 v225, v225
	v_exp_f32_e32 v226, v226
	v_exp_f32_e32 v227, v227
	v_exp_f32_e32 v234, v245
	v_exp_f32_e32 v235, v246
	s_waitcnt lgkmcnt(2)
	v_mfma_f32_32x32x16_bf16 v[64:79], v[68:71], v[100:103], 0
	s_waitcnt lgkmcnt(0)
	v_mfma_f32_32x32x16_bf16 v[64:79], v[230:233], v[108:111], v[64:79]
	v_mfma_f32_32x32x16_bf16 v[80:95], v[214:217], v[108:111], v[80:95]
	ds_read_b128 v[214:217], v198 offset:32768
	ds_read_b128 v[230:233], v200 offset:40960
	s_waitcnt lgkmcnt(0)
	v_mfma_f32_32x32x16_bf16 v[64:79], v[230:233], v[96:99], v[64:79]
	v_mfma_f32_32x32x16_bf16 v[80:95], v[214:217], v[96:99], v[80:95]
	ds_read_b128 v[214:217], v199 offset:32768
	ds_read_b128 v[230:233], v201 offset:40960
	s_waitcnt lgkmcnt(0)
	v_mfma_f32_32x32x16_bf16 v[64:79], v[230:233], v[104:107], v[64:79]
	v_mfma_f32_32x32x16_bf16 v[80:95], v[214:217], v[104:107], v[80:95]
	ds_read_b128 v[214:217], v202 offset:32768
	ds_read_b128 v[230:233], v203 offset:40960
	s_waitcnt lgkmcnt(0)
	v_mfma_f32_32x32x16_bf16 v[64:79], v[230:233], v[116:119], v[64:79]
	v_mfma_f32_32x32x16_bf16 v[80:95], v[214:217], v[116:119], v[80:95]
	ds_read_b128 v[214:217], v204 offset:32768
	ds_read_b128 v[230:233], v205 offset:40960
	s_waitcnt lgkmcnt(0)
	v_mfma_f32_32x32x16_bf16 v[64:79], v[230:233], v[124:127], v[64:79]
	v_mfma_f32_32x32x16_bf16 v[80:95], v[214:217], v[124:127], v[80:95]
	ds_read_b128 v[214:217], v206 offset:32768
	ds_read_b128 v[230:233], v208 offset:40960
	s_waitcnt lgkmcnt(0)
	v_mfma_f32_32x32x16_bf16 v[64:79], v[230:233], v[112:115], v[64:79]
	v_mfma_f32_32x32x16_bf16 v[80:95], v[214:217], v[112:115], v[80:95]
	ds_read_b128 v[214:217], v207 offset:32768
	ds_read_b128 v[230:233], v209 offset:40960
	s_waitcnt lgkmcnt(0)
	v_mfma_f32_32x32x16_bf16 v[64:79], v[230:233], v[120:123], v[64:79]
	v_exp_f32_e32 v231, v238
	v_exp_f32_e32 v238, v221
	v_add_f32_e32 v221, 0, v160
	v_add_f32_e32 v221, v175, v221
	v_add_f32_e32 v221, v161, v221
	v_add_f32_e32 v221, v174, v221
	v_add_f32_e32 v221, v162, v221
	v_add_f32_e32 v221, v173, v221
	v_add_f32_e32 v221, v163, v221
	v_add_f32_e32 v221, v172, v221
	v_add_f32_e32 v221, v164, v221
	v_add_f32_e32 v221, v171, v221
	v_add_f32_e32 v221, v165, v221
	v_add_f32_e32 v221, v170, v221
	v_mfma_f32_32x32x16_bf16 v[80:95], v[214:217], v[120:123], v[80:95]
	v_exp_f32_e32 v214, v240
	v_add_f32_e32 v221, v166, v221
	v_exp_f32_e32 v215, v241
	v_add_f32_e32 v221, v169, v221
	v_exp_f32_e32 v216, v242
	v_add_f32_e32 v221, v167, v221
	v_exp_f32_e32 v217, v243
	v_add_f32_e32 v221, v168, v221
	v_exp_f32_e32 v230, v244
	v_add_f32_e32 v221, v214, v221
	v_add_f32_e32 v221, v215, v221
	v_add_f32_e32 v221, v216, v221
	v_add_f32_e32 v221, v217, v221
	v_add_f32_e32 v221, v230, v221
	v_add_f32_e32 v221, v223, v221
	v_add_f32_e32 v221, v224, v221
	v_exp_f32_e32 v232, v239
	v_add_f32_e32 v221, v225, v221
	v_exp_f32_e32 v233, v222
	v_add_f32_e32 v221, v226, v221
	v_add_f32_e32 v221, v227, v221
	v_add_f32_e32 v221, v231, v221
	v_add_f32_e32 v221, v232, v221
	v_add_f32_e32 v221, v233, v221
	v_add_f32_e32 v221, v234, v221
	v_add_f32_e32 v221, v235, v221
	v_add_f32_e32 v221, v238, v221
	v_mov_b32_e32 v222, v221
	v_cvt_pk_bf16_f32 v160, v160, v175
	v_cvt_pk_bf16_f32 v161, v161, v174
	v_cvt_pk_bf16_f32 v162, v162, v173
	v_cvt_pk_bf16_f32 v163, v163, v172
	v_cvt_pk_bf16_f32 v164, v164, v171
	v_cvt_pk_bf16_f32 v165, v165, v170
	v_cvt_pk_bf16_f32 v166, v166, v169
	v_cvt_pk_bf16_f32 v167, v167, v168
	v_cvt_pk_bf16_f32 v168, v214, v215
	v_cvt_pk_bf16_f32 v169, v216, v217
	v_cvt_pk_bf16_f32 v170, v230, v223
	v_cvt_pk_bf16_f32 v171, v224, v225
	v_cvt_pk_bf16_f32 v172, v226, v227
	v_cvt_pk_bf16_f32 v173, v231, v232
	v_cvt_pk_bf16_f32 v174, v233, v234
	v_cvt_pk_bf16_f32 v175, v235, v238
	s_nop 1
	v_permlane32_swap_b32_e32 v221, v222
	v_permlane32_swap_b32_e32 v160, v162
	v_permlane32_swap_b32_e32 v161, v163
	v_permlane32_swap_b32_e32 v164, v166
	v_permlane32_swap_b32_e32 v165, v167
	v_permlane32_swap_b32_e32 v168, v170
	v_permlane32_swap_b32_e32 v169, v171
	v_permlane32_swap_b32_e32 v172, v174
	v_permlane32_swap_b32_e32 v173, v175
	s_cmp_ge_i32 s28, s30
	s_cbranch_scc1 .LBB0_1102
	s_ashr_i32 s15, s14, 31
	s_mul_i32 s2, s14, 0x1400
	s_mul_hi_i32 s3, s14, 0x1400
	s_add_u32 s2, s12, s2
	s_addc_u32 s3, s13, s3
	s_lshl_b64 s[34:35], s[14:15], 9
	s_add_u32 s34, s10, s34
	v_lshl_add_u64 v[128:129], v[212:213], 1, s[2:3]
	s_addc_u32 s35, s11, s35
	v_add_co_u32_e32 v132, vcc, 0x28000, v128
	v_lshl_add_u64 v[136:137], v[176:177], 1, s[34:35]
	s_nop 0
	v_addc_co_u32_e32 v133, vcc, 0, v129, vcc
	v_add_co_u32_e32 v140, vcc, 0x4000, v136
	global_load_dwordx4 v[128:131], v[128:129], off offset:2560
	s_nop 0
	global_load_dwordx4 v[132:135], v[132:133], off offset:2560
	v_addc_co_u32_e32 v141, vcc, 0, v137, vcc
	global_load_dwordx4 v[136:139], v[136:137], off
	s_nop 0
	global_load_dwordx4 v[140:143], v[140:141], off
.LBB0_1102:
	ds_read_b64_tr_b16 v[214:215], v188 offset:0
	ds_read_b64_tr_b16 v[216:217], v188 offset:0x800
	ds_read_b64_tr_b16 v[224:225], v188 offset:0x200
	ds_read_b64_tr_b16 v[226:227], v188 offset:0xa00
	ds_read_b64_tr_b16 v[230:231], v188 offset:0x400
	ds_read_b64_tr_b16 v[232:233], v188 offset:0xc00
	ds_read_b64_tr_b16 v[238:239], v188 offset:0x600
	ds_read_b64_tr_b16 v[240:241], v188 offset:0xe00
	s_waitcnt lgkmcnt(6)
	s_nop 0
	v_mfma_f32_32x32x16_bf16 v[0:15], v[160:163], v[214:217], v[0:15]
	ds_read_b64_tr_b16 v[214:215], v188 offset:0x1000
	ds_read_b64_tr_b16 v[216:217], v188 offset:0x1800
	s_waitcnt lgkmcnt(6)
	v_mfma_f32_32x32x16_bf16 v[48:63], v[160:163], v[224:227], v[48:63]
	ds_read_b64_tr_b16 v[224:225], v188 offset:0x1200
	ds_read_b64_tr_b16 v[226:227], v188 offset:0x1a00
	s_waitcnt lgkmcnt(6)
	v_mfma_f32_32x32x16_bf16 v[32:47], v[160:163], v[230:233], v[32:47]
	ds_read_b64_tr_b16 v[230:231], v188 offset:0x1400
	ds_read_b64_tr_b16 v[232:233], v188 offset:0x1c00
	s_waitcnt lgkmcnt(6)
	v_mfma_f32_32x32x16_bf16 v[16:31], v[160:163], v[238:241], v[16:31]
	ds_read_b64_tr_b16 v[238:239], v188 offset:0x1600
	ds_read_b64_tr_b16 v[240:241], v188 offset:0x1e00
	s_waitcnt lgkmcnt(6)
	v_mfma_f32_32x32x16_bf16 v[0:15], v[164:167], v[214:217], v[0:15]
	ds_read_b64_tr_b16 v[214:215], v188 offset:0x2000
	ds_read_b64_tr_b16 v[216:217], v188 offset:0x2800
	v_max_f32_e32 v160, v81, v81
	v_max_f32_e32 v161, v80, v80
	v_max_f32_e32 v160, v161, v160
	v_max3_f32 v160, v160, v82, v83
	v_max3_f32 v160, v160, v84, v85
	v_max3_f32 v160, v160, v86, v87
	v_max3_f32 v160, v160, v88, v89
	v_max3_f32 v160, v160, v90, v91
	s_waitcnt lgkmcnt(6)
	v_mfma_f32_32x32x16_bf16 v[48:63], v[164:167], v[224:227], v[48:63]
	ds_read_b64_tr_b16 v[224:225], v188 offset:0x2200
	ds_read_b64_tr_b16 v[226:227], v188 offset:0x2a00
	s_waitcnt lgkmcnt(6)
	v_mfma_f32_32x32x16_bf16 v[32:47], v[164:167], v[230:233], v[32:47]
	ds_read_b64_tr_b16 v[230:231], v188 offset:0x2400
	ds_read_b64_tr_b16 v[232:233], v188 offset:0x2c00
	v_max3_f32 v160, v160, v92, v93
	v_max3_f32 v160, v160, v94, v95
	v_max3_f32 v160, v160, v64, v65
	v_max3_f32 v160, v160, v66, v67
	v_max3_f32 v160, v160, v68, v69
	v_max3_f32 v160, v160, v70, v71
	v_max3_f32 v160, v160, v72, v73
	v_max3_f32 v160, v160, v74, v75
	s_waitcnt lgkmcnt(6)
	v_mfma_f32_32x32x16_bf16 v[16:31], v[164:167], v[238:241], v[16:31]
	ds_read_b64_tr_b16 v[238:239], v188 offset:0x2600
	ds_read_b64_tr_b16 v[240:241], v188 offset:0x2e00
	s_waitcnt lgkmcnt(6)
	v_mfma_f32_32x32x16_bf16 v[0:15], v[168:171], v[214:217], v[0:15]
	ds_read_b64_tr_b16 v[214:215], v188 offset:0x3000
	ds_read_b64_tr_b16 v[216:217], v188 offset:0x3800
	v_max3_f32 v160, v160, v76, v77
	v_max3_f32 v160, v160, v78, v79
	v_mov_b32_e32 v161, v160
	s_nop 1
	v_permlane32_swap_b32_e32 v160, v161
	v_max_f32_e32 v161, v161, v161
	v_max_f32_e32 v160, v160, v160
	v_max_f32_e32 v160, v160, v161
	s_waitcnt lgkmcnt(6)
	v_mfma_f32_32x32x16_bf16 v[48:63], v[168:171], v[224:227], v[48:63]
	ds_read_b64_tr_b16 v[224:225], v188 offset:0x3200
	ds_read_b64_tr_b16 v[226:227], v188 offset:0x3a00
	s_waitcnt lgkmcnt(6)
	v_mfma_f32_32x32x16_bf16 v[32:47], v[168:171], v[230:233], v[32:47]
	ds_read_b64_tr_b16 v[230:231], v188 offset:0x3400
	ds_read_b64_tr_b16 v[232:233], v188 offset:0x3c00
	v_sub_f32_e32 v161, v160, v220
	v_cmp_ge_f32_e32 vcc, s90, v161
	v_max_f32_e32 v161, v220, v220
	v_max_f32_e32 v161, v161, v160
	v_sub_f32_e32 v160, v220, v161
	v_mul_f32_e32 v160, 0x3e0293ee, v160
	v_exp_f32_e32 v160, v160
	s_cmp_eq_u64 vcc, exec
	s_cselect_b64 s[38:39], -1, 0
	s_waitcnt lgkmcnt(6)
	v_mfma_f32_32x32x16_bf16 v[16:31], v[168:171], v[238:241], v[16:31]
	ds_read_b64_tr_b16 v[238:239], v188 offset:0x3600
	ds_read_b64_tr_b16 v[240:241], v188 offset:0x3e00
	v_cndmask_b32_e64 v162, v161, v220, s[38:39]
	v_mul_f32_e32 v163, 0xbe0293ee, v162
	v_fmamk_f32 v80, v80, 0x3e0293ee, v163
	v_fmamk_f32 v81, v81, 0x3e0293ee, v163
	v_fmamk_f32 v82, v82, 0x3e0293ee, v163
	v_fmamk_f32 v83, v83, 0x3e0293ee, v163
	v_fmamk_f32 v84, v84, 0x3e0293ee, v163
	v_fmamk_f32 v85, v85, 0x3e0293ee, v163
	v_fmamk_f32 v86, v86, 0x3e0293ee, v163
	v_fmamk_f32 v87, v87, 0x3e0293ee, v163
	s_waitcnt lgkmcnt(6)
	v_mfma_f32_32x32x16_bf16 v[0:15], v[172:175], v[214:217], v[0:15]
	v_fmamk_f32 v88, v88, 0x3e0293ee, v163
	v_fmamk_f32 v89, v89, 0x3e0293ee, v163
	v_fmamk_f32 v90, v90, 0x3e0293ee, v163
	v_fmamk_f32 v91, v91, 0x3e0293ee, v163
	v_fmamk_f32 v92, v92, 0x3e0293ee, v163
	v_fmamk_f32 v93, v93, 0x3e0293ee, v163
	v_fmamk_f32 v94, v94, 0x3e0293ee, v163
	s_waitcnt lgkmcnt(0)
	s_barrier
	v_mfma_f32_32x32x16_bf16 v[48:63], v[172:175], v[224:227], v[48:63]
	s_waitcnt vmcnt(4)
	v_cndmask_b32_e64 v160, v160, 1.0, s[38:39]
	v_cmp_gt_f32_e32 vcc, 1.0, v160
	s_waitcnt vmcnt(3)
	ds_write_b128 v190, v[144:147] offset:16384
	s_waitcnt vmcnt(2)
	ds_write_b128 v191, v[148:151] offset:16384
	v_mfma_f32_32x32x16_bf16 v[32:47], v[172:175], v[230:233], v[32:47]
	s_waitcnt vmcnt(1)
	ds_write_b128 v192, v[152:155] offset:49152
	s_waitcnt vmcnt(0)
	ds_write_b128 v193, v[156:159] offset:49152
	v_mfma_f32_32x32x16_bf16 v[16:31], v[172:175], v[238:241], v[16:31]
	s_cbranch_vccz .LBB0_1106
	s_and_saveexec_b64 s[2:3], s[36:37]
	ds_write_b32 v186, v160 offset:128
	s_or_b64 exec, exec, s[2:3]
	s_waitcnt lgkmcnt(0)
	v_add_u32_e32 v156, s27, v185
	ds_read_b128 v[144:147], v156 offset:224
	ds_read_b128 v[148:151], v156 offset:192
	ds_read_b128 v[152:155], v156 offset:160
	ds_read_b128 v[156:159], v156 offset:128
	s_waitcnt lgkmcnt(3)
	v_pk_mul_f32 v[12:13], v[12:13], v[144:145]
	s_waitcnt lgkmcnt(2)
	v_pk_mul_f32 v[8:9], v[8:9], v[148:149]
	s_waitcnt lgkmcnt(1)
	v_pk_mul_f32 v[4:5], v[4:5], v[152:153]
	v_pk_mul_f32 v[14:15], v[14:15], v[146:147]
	v_pk_mul_f32 v[10:11], v[10:11], v[150:151]
	v_pk_mul_f32 v[6:7], v[6:7], v[154:155]
	s_waitcnt lgkmcnt(0)
	v_pk_mul_f32 v[2:3], v[2:3], v[158:159]
	v_pk_mul_f32 v[0:1], v[0:1], v[156:157]
	v_pk_mul_f32 v[60:61], v[60:61], v[144:145]
	v_pk_mul_f32 v[56:57], v[56:57], v[148:149]
	v_pk_mul_f32 v[52:53], v[52:53], v[152:153]
	v_pk_mul_f32 v[62:63], v[62:63], v[146:147]
	v_pk_mul_f32 v[58:59], v[58:59], v[150:151]
	v_pk_mul_f32 v[54:55], v[54:55], v[154:155]
	v_pk_mul_f32 v[50:51], v[50:51], v[158:159]
	v_pk_mul_f32 v[48:49], v[48:49], v[156:157]
	v_pk_mul_f32 v[44:45], v[44:45], v[144:145]
	v_pk_mul_f32 v[40:41], v[40:41], v[148:149]
	v_pk_mul_f32 v[36:37], v[36:37], v[152:153]
	v_pk_mul_f32 v[46:47], v[46:47], v[146:147]
	v_pk_mul_f32 v[42:43], v[42:43], v[150:151]
	v_pk_mul_f32 v[38:39], v[38:39], v[154:155]
	v_pk_mul_f32 v[34:35], v[34:35], v[158:159]
	v_pk_mul_f32 v[32:33], v[32:33], v[156:157]
	v_pk_mul_f32 v[28:29], v[28:29], v[144:145]
	v_pk_mul_f32 v[24:25], v[24:25], v[148:149]
	v_pk_mul_f32 v[20:21], v[20:21], v[152:153]
	v_pk_mul_f32 v[30:31], v[30:31], v[146:147]
	v_pk_mul_f32 v[26:27], v[26:27], v[150:151]
	v_pk_mul_f32 v[22:23], v[22:23], v[154:155]
	v_pk_mul_f32 v[18:19], v[18:19], v[158:159]
	v_pk_mul_f32 v[16:17], v[16:17], v[156:157]
.LBB0_1106:
	v_cndmask_b32_e64 v168, v161, v220, s[38:39]
	v_mul_f32_e32 v150, 0xbe0293ee, v168
	v_mov_b32_e32 v151, v150
	v_fmac_f32_e32 v151, 0x3e0293ee, v95
	v_exp_f32_e32 v175, v80
	v_exp_f32_e32 v223, v81
	v_exp_f32_e32 v161, v82
	v_exp_f32_e32 v220, v83
	v_exp_f32_e32 v162, v84
	v_exp_f32_e32 v174, v85
	v_exp_f32_e32 v163, v86
	v_exp_f32_e32 v173, v87
	v_exp_f32_e32 v164, v88
	v_exp_f32_e32 v172, v89
	v_exp_f32_e32 v165, v90
	v_exp_f32_e32 v171, v91
	v_exp_f32_e32 v166, v92
	v_exp_f32_e32 v170, v93
	v_exp_f32_e32 v167, v94
	v_exp_f32_e32 v169, v151
	v_pk_fma_f32 v[156:157], v[64:65], s[94:95], v[150:151] op_sel_hi:[1,0,0]
	v_add_f32_e32 v64, v211, v218
	v_fmac_f32_e32 v64, v210, v187
	v_add_f32_e32 v187, v221, v222
	s_add_i32 s28, s28, 2
	s_addk_i32 s14, 0x80
	s_mov_b64 s[2:3], 0x10000
	v_pk_fma_f32 v[154:155], v[66:67], s[94:95], v[150:151] op_sel_hi:[1,0,0]
	v_pk_fma_f32 v[148:149], v[68:69], s[94:95], v[150:151] op_sel_hi:[1,0,0]
	v_pk_fma_f32 v[146:147], v[70:71], s[94:95], v[150:151] op_sel_hi:[1,0,0]
	v_pk_fma_f32 v[144:145], v[72:73], s[94:95], v[150:151] op_sel_hi:[1,0,0]
	v_pk_fma_f32 v[158:159], v[74:75], s[94:95], v[150:151] op_sel_hi:[1,0,0]
	v_pk_fma_f32 v[152:153], v[76:77], s[94:95], v[150:151] op_sel_hi:[1,0,0]
	v_pk_fma_f32 v[150:151], v[78:79], s[94:95], v[150:151] op_sel_hi:[1,0,0]
	v_fmac_f32_e32 v187, v64, v219
	v_lshl_add_u64 v[178:179], v[178:179], 0, s[2:3]
	s_cmp_ge_i32 s28, s29
	v_lshl_add_u64 v[180:181], v[180:181], 0, s[64:65]
	s_waitcnt lgkmcnt(0)
	s_barrier
	s_cbranch_scc1 .LBB0_1108
	v_mov_b32_e32 v210, v160
	s_branch .LBB0_1096

.LBB0_1135:
	ds_read_b128 v[64:67], v194 offset:57344
	ds_read_b128 v[68:71], v212 offset:57344
	ds_read_b128 v[214:217], v197 offset:57344
	ds_read_b128 v[230:233], v211 offset:57344
	v_add_f32_e32 v164, 0, v165
	v_add_f32_e32 v164, v224, v164
	s_waitcnt lgkmcnt(3)
	v_mfma_f32_32x32x16_bf16 v[80:95], v[64:67], v[140:143], 0
	v_add_f32_e32 v164, v166, v164
	v_add_f32_e32 v164, v225, v164
	v_add_f32_e32 v164, v223, v164
	v_add_f32_e32 v164, v226, v164
	v_add_f32_e32 v164, v167, v164
	v_add_f32_e32 v164, v222, v164
	v_add_f32_e32 v164, v172, v164
	s_waitcnt lgkmcnt(2)
	v_mfma_f32_32x32x16_bf16 v[64:79], v[68:71], v[140:143], 0
	v_add_f32_e32 v164, v174, v164
	v_add_f32_e32 v164, v173, v164
	v_add_f32_e32 v164, v175, v164
	v_exp_f32_e32 v158, v158
	v_add_f32_e32 v164, v160, v164
	v_exp_f32_e32 v159, v159
	v_add_f32_e32 v164, v162, v164
	s_waitcnt lgkmcnt(1)
	v_mfma_f32_32x32x16_bf16 v[80:95], v[214:217], v[136:139], v[80:95]
	v_exp_f32_e32 v156, v156
	v_add_f32_e32 v164, v161, v164
	v_exp_f32_e32 v157, v157
	v_add_f32_e32 v164, v163, v164
	v_exp_f32_e32 v152, v152
	v_add_f32_e32 v164, v158, v164
	v_exp_f32_e32 v153, v153
	s_waitcnt lgkmcnt(0)
	v_mfma_f32_32x32x16_bf16 v[64:79], v[230:233], v[136:139], v[64:79]
	ds_read_b128 v[214:217], v196 offset:57344
	ds_read_b128 v[230:233], v210 offset:57344
	v_add_f32_e32 v164, v159, v164
	v_exp_f32_e32 v148, v148
	v_add_f32_e32 v164, v156, v164
	v_exp_f32_e32 v149, v149
	v_add_f32_e32 v164, v157, v164
	v_exp_f32_e32 v146, v146
	s_waitcnt lgkmcnt(1)
	v_mfma_f32_32x32x16_bf16 v[80:95], v[214:217], v[132:135], v[80:95]
	v_add_f32_e32 v164, v152, v164
	v_exp_f32_e32 v147, v147
	v_add_f32_e32 v164, v153, v164
	v_exp_f32_e32 v154, v154
	v_add_f32_e32 v164, v148, v164
	v_exp_f32_e32 v155, v155
	v_add_f32_e32 v164, v149, v164
	s_waitcnt lgkmcnt(0)
	v_mfma_f32_32x32x16_bf16 v[64:79], v[230:233], v[132:135], v[64:79]
	ds_read_b128 v[214:217], v195 offset:57344
	ds_read_b128 v[230:233], v209 offset:57344
	v_exp_f32_e32 v150, v150
	v_add_f32_e32 v164, v146, v164
	v_exp_f32_e32 v151, v151
	v_add_f32_e32 v164, v147, v164
	v_exp_f32_e32 v144, v144
	v_add_f32_e32 v164, v154, v164
	s_waitcnt lgkmcnt(1)
	v_mfma_f32_32x32x16_bf16 v[80:95], v[214:217], v[128:131], v[80:95]
	v_exp_f32_e32 v145, v145
	v_add_f32_e32 v164, v155, v164
	v_add_f32_e32 v164, v150, v164
	v_add_f32_e32 v164, v151, v164
	v_add_f32_e32 v164, v144, v164
	v_add_f32_e32 v219, v145, v164
	v_mov_b32_e32 v220, v219
	s_waitcnt lgkmcnt(0)
	v_mfma_f32_32x32x16_bf16 v[64:79], v[230:233], v[128:131], v[64:79]
	ds_read_b128 v[214:217], v193 offset:57344
	ds_read_b128 v[230:233], v208 offset:57344
	v_permlane32_swap_b32_e32 v219, v220
	s_waitcnt lgkmcnt(1)
	v_mfma_f32_32x32x16_bf16 v[80:95], v[214:217], v[124:127], v[80:95]
	s_waitcnt lgkmcnt(0)
	v_mfma_f32_32x32x16_bf16 v[64:79], v[230:233], v[124:127], v[64:79]
	ds_read_b128 v[214:217], v192 offset:57344
	ds_read_b128 v[230:233], v206 offset:57344
	s_waitcnt lgkmcnt(1)
	v_mfma_f32_32x32x16_bf16 v[80:95], v[214:217], v[120:123], v[80:95]
	s_waitcnt lgkmcnt(0)
	v_mfma_f32_32x32x16_bf16 v[64:79], v[230:233], v[120:123], v[64:79]
	ds_read_b128 v[214:217], v186 offset:57344
	ds_read_b128 v[230:233], v205 offset:57344
	s_waitcnt lgkmcnt(1)
	v_mfma_f32_32x32x16_bf16 v[80:95], v[214:217], v[116:119], v[80:95]
	s_waitcnt lgkmcnt(0)
	v_mfma_f32_32x32x16_bf16 v[64:79], v[230:233], v[116:119], v[64:79]
	ds_read_b128 v[214:217], v189 offset:57344
	ds_read_b128 v[230:233], v204 offset:57344
	s_waitcnt lgkmcnt(1)
	v_mfma_f32_32x32x16_bf16 v[80:95], v[214:217], v[112:115], v[80:95]
	s_waitcnt lgkmcnt(0)
	v_mfma_f32_32x32x16_bf16 v[64:79], v[230:233], v[112:115], v[64:79]
	ds_read_b128 v[214:217], v190 offset:57344
	ds_read_b128 v[230:233], v203 offset:57344
	s_waitcnt lgkmcnt(1)
	v_mfma_f32_32x32x16_bf16 v[80:95], v[214:217], v[108:111], v[80:95]
	s_waitcnt lgkmcnt(0)
	v_mfma_f32_32x32x16_bf16 v[64:79], v[230:233], v[108:111], v[64:79]
	ds_read_b128 v[214:217], v188 offset:57344
	ds_read_b128 v[230:233], v202 offset:57344
	s_waitcnt lgkmcnt(1)
	v_mfma_f32_32x32x16_bf16 v[80:95], v[214:217], v[104:107], v[80:95]
	s_waitcnt lgkmcnt(0)
	v_mfma_f32_32x32x16_bf16 v[64:79], v[230:233], v[104:107], v[64:79]
	ds_read_b128 v[214:217], v199 offset:57344
	ds_read_b128 v[230:233], v201 offset:57344
	s_waitcnt lgkmcnt(1)
	v_mfma_f32_32x32x16_bf16 v[80:95], v[214:217], v[100:103], v[80:95]
	s_waitcnt lgkmcnt(0)
	v_mfma_f32_32x32x16_bf16 v[64:79], v[230:233], v[100:103], v[64:79]
	ds_read_b128 v[214:217], v198 offset:57344
	ds_read_b128 v[230:233], v200 offset:57344
	v_cvt_pk_bf16_f32 v164, v165, v224
	v_cvt_pk_bf16_f32 v165, v166, v225
	v_cvt_pk_bf16_f32 v166, v223, v226
	v_cvt_pk_bf16_f32 v167, v167, v222
	s_nop 0
	v_permlane32_swap_b32_e32 v164, v166
	s_waitcnt lgkmcnt(1)
	v_mfma_f32_32x32x16_bf16 v[80:95], v[214:217], v[96:99], v[80:95]
	v_cvt_pk_bf16_f32 v214, v172, v174
	v_cvt_pk_bf16_f32 v215, v173, v175
	v_cvt_pk_bf16_f32 v216, v160, v162
	v_cvt_pk_bf16_f32 v217, v161, v163
	v_cvt_pk_bf16_f32 v222, v158, v159
	v_cvt_pk_bf16_f32 v223, v156, v157
	v_cvt_pk_bf16_f32 v224, v152, v153
	s_waitcnt lgkmcnt(0)
	v_mfma_f32_32x32x16_bf16 v[64:79], v[230:233], v[96:99], v[64:79]
	v_cvt_pk_bf16_f32 v225, v148, v149
	v_cvt_pk_bf16_f32 v230, v146, v147
	v_cvt_pk_bf16_f32 v231, v154, v155
	v_cvt_pk_bf16_f32 v232, v150, v151
	v_cvt_pk_bf16_f32 v233, v144, v145
	v_permlane32_swap_b32_e32 v165, v167
	v_permlane32_swap_b32_e32 v214, v216
	v_permlane32_swap_b32_e32 v215, v217
	v_permlane32_swap_b32_e32 v222, v224
	v_permlane32_swap_b32_e32 v223, v225
	v_permlane32_swap_b32_e32 v230, v232
	v_permlane32_swap_b32_e32 v231, v233
	v_lshl_add_u64 v[172:173], s[44:45], 0, v[170:171]
	s_mov_b32 s2, 0x4bf80000
	v_add_co_u32_e32 v148, vcc, s2, v172
	s_mov_b32 s2, 0x4bfa0000
	s_nop 0
	v_addc_co_u32_e32 v149, vcc, 0, v173, vcc
	v_add_co_u32_e32 v152, vcc, s2, v172
	v_lshl_add_u64 v[174:175], s[44:45], 0, v[168:169]
	s_nop 0
	v_addc_co_u32_e32 v153, vcc, 0, v173, vcc
	global_load_dwordx4 v[144:147], v[148:149], off offset:256
	s_nop 0
	global_load_dwordx4 v[148:151], v[148:149], off
	s_nop 0
	global_load_dwordx4 v[156:159], v[152:153], off offset:256
	s_nop 0
	global_load_dwordx4 v[152:155], v[152:153], off
	s_mov_b32 s2, 0x45404000
	v_add_co_u32_e32 v160, vcc, s2, v174
	s_nop 1
	v_addc_co_u32_e32 v161, vcc, 0, v175, vcc
	global_load_dwordx4 v[160:163], v[160:161], off
	ds_read_b64_tr_b16 v[238:239], v182 offset:0
	ds_read_b64_tr_b16 v[240:241], v182 offset:0x800
	ds_read_b64_tr_b16 v[242:243], v182 offset:0x200
	ds_read_b64_tr_b16 v[244:245], v182 offset:0xa00
	ds_read_b64_tr_b16 v[246:247], v182 offset:0x400
	ds_read_b64_tr_b16 v[248:249], v182 offset:0xc00
	ds_read_b64_tr_b16 v[250:251], v182 offset:0x600
	ds_read_b64_tr_b16 v[252:253], v182 offset:0xe00
	s_waitcnt lgkmcnt(6)
	s_nop 0
	v_mfma_f32_32x32x16_bf16 v[0:15], v[164:167], v[238:241], v[0:15]
	ds_read_b64_tr_b16 v[238:239], v182 offset:0x1000
	ds_read_b64_tr_b16 v[240:241], v182 offset:0x1800
	s_waitcnt lgkmcnt(6)
	v_mfma_f32_32x32x16_bf16 v[48:63], v[164:167], v[242:245], v[48:63]
	ds_read_b64_tr_b16 v[242:243], v182 offset:0x1200
	ds_read_b64_tr_b16 v[244:245], v182 offset:0x1a00
	s_waitcnt lgkmcnt(6)
	v_mfma_f32_32x32x16_bf16 v[32:47], v[164:167], v[246:249], v[32:47]
	ds_read_b64_tr_b16 v[246:247], v182 offset:0x1400
	ds_read_b64_tr_b16 v[248:249], v182 offset:0x1c00
	s_waitcnt lgkmcnt(6)
	v_mfma_f32_32x32x16_bf16 v[16:31], v[164:167], v[250:253], v[16:31]
	ds_read_b64_tr_b16 v[250:251], v182 offset:0x1600
	ds_read_b64_tr_b16 v[252:253], v182 offset:0x1e00
	s_waitcnt lgkmcnt(6)
	v_mfma_f32_32x32x16_bf16 v[0:15], v[214:217], v[238:241], v[0:15]
	ds_read_b64_tr_b16 v[238:239], v182 offset:0x2000
	ds_read_b64_tr_b16 v[240:241], v182 offset:0x2800
	v_max_f32_e32 v164, v81, v81
	v_max_f32_e32 v165, v80, v80
	v_max_f32_e32 v164, v165, v164
	v_max3_f32 v164, v164, v82, v83
	v_max3_f32 v164, v164, v84, v85
	v_max3_f32 v164, v164, v86, v87
	v_max3_f32 v164, v164, v88, v89
	v_max3_f32 v164, v164, v90, v91
	s_waitcnt lgkmcnt(6)
	v_mfma_f32_32x32x16_bf16 v[48:63], v[214:217], v[242:245], v[48:63]
	ds_read_b64_tr_b16 v[242:243], v182 offset:0x2200
	ds_read_b64_tr_b16 v[244:245], v182 offset:0x2a00
	s_waitcnt lgkmcnt(6)
	v_mfma_f32_32x32x16_bf16 v[32:47], v[214:217], v[246:249], v[32:47]
	ds_read_b64_tr_b16 v[246:247], v182 offset:0x2400
	ds_read_b64_tr_b16 v[248:249], v182 offset:0x2c00
	v_max3_f32 v164, v164, v92, v93
	v_max3_f32 v164, v164, v94, v95
	v_max3_f32 v164, v164, v64, v65
	v_max3_f32 v164, v164, v66, v67
	v_max3_f32 v164, v164, v68, v69
	v_max3_f32 v164, v164, v70, v71
	v_max3_f32 v164, v164, v72, v73
	v_max3_f32 v164, v164, v74, v75
	s_waitcnt lgkmcnt(6)
	v_mfma_f32_32x32x16_bf16 v[16:31], v[214:217], v[250:253], v[16:31]
	ds_read_b64_tr_b16 v[250:251], v182 offset:0x2600
	ds_read_b64_tr_b16 v[252:253], v182 offset:0x2e00
	s_waitcnt lgkmcnt(6)
	v_mfma_f32_32x32x16_bf16 v[0:15], v[222:225], v[238:241], v[0:15]
	ds_read_b64_tr_b16 v[238:239], v182 offset:0x3000
	ds_read_b64_tr_b16 v[240:241], v182 offset:0x3800
	v_max3_f32 v164, v164, v76, v77
	v_max3_f32 v164, v164, v78, v79
	v_mov_b32_e32 v165, v164
	s_nop 1
	v_permlane32_swap_b32_e32 v164, v165
	v_max_f32_e32 v165, v165, v165
	v_max_f32_e32 v164, v164, v164
	v_max_f32_e32 v164, v164, v165
	s_waitcnt lgkmcnt(6)
	v_mfma_f32_32x32x16_bf16 v[48:63], v[222:225], v[242:245], v[48:63]
	ds_read_b64_tr_b16 v[242:243], v182 offset:0x3200
	ds_read_b64_tr_b16 v[244:245], v182 offset:0x3a00
	s_waitcnt lgkmcnt(6)
	v_mfma_f32_32x32x16_bf16 v[32:47], v[222:225], v[246:249], v[32:47]
	ds_read_b64_tr_b16 v[246:247], v182 offset:0x3400
	ds_read_b64_tr_b16 v[248:249], v182 offset:0x3c00
	v_sub_f32_e32 v165, v164, v207
	v_cmp_ge_f32_e32 vcc, s46, v165
	v_max_f32_e32 v165, v207, v207
	v_max_f32_e32 v164, v165, v164
	v_sub_f32_e32 v165, v207, v164
	v_mul_f32_e32 v165, 0x3dd53b94, v165
	v_exp_f32_e32 v165, v165
	s_cmp_eq_u64 vcc, exec
	s_cselect_b64 s[38:39], -1, 0
	s_waitcnt lgkmcnt(6)
	v_mfma_f32_32x32x16_bf16 v[16:31], v[222:225], v[250:253], v[16:31]
	ds_read_b64_tr_b16 v[250:251], v182 offset:0x3600
	ds_read_b64_tr_b16 v[252:253], v182 offset:0x3e00
	v_cndmask_b32_e64 v166, v164, v207, s[38:39]
	v_mul_f32_e32 v167, 0xbdd53b94, v166
	v_fmamk_f32 v80, v80, 0x3dd53b94, v167
	v_fmamk_f32 v81, v81, 0x3dd53b94, v167
	v_fmamk_f32 v82, v82, 0x3dd53b94, v167
	v_fmamk_f32 v83, v83, 0x3dd53b94, v167
	v_fmamk_f32 v84, v84, 0x3dd53b94, v167
	v_fmamk_f32 v85, v85, 0x3dd53b94, v167
	v_fmamk_f32 v86, v86, 0x3dd53b94, v167
	v_fmamk_f32 v87, v87, 0x3dd53b94, v167
	s_waitcnt lgkmcnt(6)
	v_mfma_f32_32x32x16_bf16 v[0:15], v[230:233], v[238:241], v[0:15]
	v_fmamk_f32 v88, v88, 0x3dd53b94, v167
	v_fmamk_f32 v89, v89, 0x3dd53b94, v167
	v_fmamk_f32 v90, v90, 0x3dd53b94, v167
	v_fmamk_f32 v91, v91, 0x3dd53b94, v167
	v_fmamk_f32 v92, v92, 0x3dd53b94, v167
	v_fmamk_f32 v93, v93, 0x3dd53b94, v167
	v_fmamk_f32 v94, v94, 0x3dd53b94, v167
	v_fmamk_f32 v95, v95, 0x3dd53b94, v167
	s_waitcnt lgkmcnt(0)
	s_barrier
	v_mfma_f32_32x32x16_bf16 v[48:63], v[230:233], v[242:245], v[48:63]
	s_waitcnt vmcnt(0)
	v_cndmask_b32_e64 v221, v165, 1.0, s[38:39]
	v_cmp_gt_f32_e32 vcc, 1.0, v221
	s_waitcnt vmcnt(4)
	ds_write_b128 v183, v[144:147]
	s_waitcnt vmcnt(2)
	ds_write_b128 v184, v[156:159]
	v_mfma_f32_32x32x16_bf16 v[32:47], v[230:233], v[246:249], v[32:47]
	ds_write_b128 v185, v[148:151] offset:32768
	s_waitcnt vmcnt(1)
	ds_write_b128 v187, v[152:155] offset:32768
	s_waitcnt vmcnt(0)
	ds_write_b128 v191, v[160:163] offset:32768
	v_mfma_f32_32x32x16_bf16 v[16:31], v[230:233], v[250:253], v[16:31]
	s_cbranch_vccz .LBB0_1139
	s_and_saveexec_b64 s[2:3], s[36:37]
	ds_write_b32 v179, v221 offset:128
	s_or_b64 exec, exec, s[2:3]
	s_waitcnt lgkmcnt(0)
	v_add_u32_e32 v156, s14, v178
	ds_read_b128 v[144:147], v156 offset:224
	ds_read_b128 v[148:151], v156 offset:192
	ds_read_b128 v[152:155], v156 offset:160
	ds_read_b128 v[156:159], v156 offset:128
	s_waitcnt lgkmcnt(3)
	v_pk_mul_f32 v[12:13], v[12:13], v[144:145]
	s_waitcnt lgkmcnt(2)
	v_pk_mul_f32 v[8:9], v[8:9], v[148:149]
	s_waitcnt lgkmcnt(1)
	v_pk_mul_f32 v[4:5], v[4:5], v[152:153]
	v_pk_mul_f32 v[14:15], v[14:15], v[146:147]
	v_pk_mul_f32 v[10:11], v[10:11], v[150:151]
	v_pk_mul_f32 v[6:7], v[6:7], v[154:155]
	s_waitcnt lgkmcnt(0)
	v_pk_mul_f32 v[2:3], v[2:3], v[158:159]
	v_pk_mul_f32 v[0:1], v[0:1], v[156:157]
	v_pk_mul_f32 v[60:61], v[60:61], v[144:145]
	v_pk_mul_f32 v[56:57], v[56:57], v[148:149]
	v_pk_mul_f32 v[52:53], v[52:53], v[152:153]
	v_pk_mul_f32 v[62:63], v[62:63], v[146:147]
	v_pk_mul_f32 v[58:59], v[58:59], v[150:151]
	v_pk_mul_f32 v[54:55], v[54:55], v[154:155]
	v_pk_mul_f32 v[50:51], v[50:51], v[158:159]
	v_pk_mul_f32 v[48:49], v[48:49], v[156:157]
	v_pk_mul_f32 v[44:45], v[44:45], v[144:145]
	v_pk_mul_f32 v[40:41], v[40:41], v[148:149]
	v_pk_mul_f32 v[36:37], v[36:37], v[152:153]
	v_pk_mul_f32 v[46:47], v[46:47], v[146:147]
	v_pk_mul_f32 v[42:43], v[42:43], v[150:151]
	v_pk_mul_f32 v[38:39], v[38:39], v[154:155]
	v_pk_mul_f32 v[34:35], v[34:35], v[158:159]
	v_pk_mul_f32 v[32:33], v[32:33], v[156:157]
	v_pk_mul_f32 v[28:29], v[28:29], v[144:145]
	v_pk_mul_f32 v[24:25], v[24:25], v[148:149]
	v_pk_mul_f32 v[20:21], v[20:21], v[152:153]
	v_pk_mul_f32 v[30:31], v[30:31], v[146:147]
	v_pk_mul_f32 v[26:27], v[26:27], v[150:151]
	v_pk_mul_f32 v[22:23], v[22:23], v[154:155]
	v_pk_mul_f32 v[18:19], v[18:19], v[158:159]
	v_pk_mul_f32 v[16:17], v[16:17], v[156:157]
.LBB0_1139:
	v_cndmask_b32_e64 v207, v164, v207, s[38:39]
	v_mul_f32_e32 v160, 0xbdd53b94, v207
	v_fmamk_f32 v227, v68, 0x3dd53b94, v160
	v_fmamk_f32 v164, v71, 0x3dd53b94, v160
	v_fmamk_f32 v165, v72, 0x3dd53b94, v160
	v_fmamk_f32 v238, v77, 0x3dd53b94, v160
	v_fmamk_f32 v223, v64, 0x3dd53b94, v160
	v_fmamk_f32 v224, v65, 0x3dd53b94, v160
	v_fmamk_f32 v225, v66, 0x3dd53b94, v160
	v_fmamk_f32 v226, v67, 0x3dd53b94, v160
	v_fmamk_f32 v162, v69, 0x3dd53b94, v160
	v_fmamk_f32 v163, v70, 0x3dd53b94, v160
	v_fmamk_f32 v166, v73, 0x3dd53b94, v160
	v_fmamk_f32 v167, v74, 0x3dd53b94, v160
	v_fmamk_f32 v222, v75, 0x3dd53b94, v160
	v_fmamk_f32 v161, v76, 0x3dd53b94, v160
	v_exp_f32_e32 v157, v80
	v_exp_f32_e32 v159, v81
	v_exp_f32_e32 v155, v82
	v_exp_f32_e32 v158, v83
	v_exp_f32_e32 v154, v84
	v_exp_f32_e32 v156, v85
	v_exp_f32_e32 v152, v86
	v_exp_f32_e32 v153, v87
	v_exp_f32_e32 v149, v88
	v_exp_f32_e32 v151, v89
	v_exp_f32_e32 v148, v90
	v_exp_f32_e32 v150, v91
	v_exp_f32_e32 v145, v92
	v_exp_f32_e32 v147, v93
	v_exp_f32_e32 v144, v94
	v_exp_f32_e32 v146, v95
	v_fmamk_f32 v239, v78, 0x3dd53b94, v160
	v_fmac_f32_e32 v160, 0x3dd53b94, v79
	s_waitcnt lgkmcnt(0)
	s_barrier
	ds_read_b128 v[64:67], v194 offset:32768
	ds_read_b128 v[68:71], v194 offset:45056
	ds_read_b128 v[214:217], v197 offset:32768
	ds_read_b128 v[230:233], v197 offset:45056
	v_exp_f32_e32 v223, v223
	v_exp_f32_e32 v224, v224
	s_waitcnt lgkmcnt(3)
	v_mfma_f32_32x32x16_bf16 v[80:95], v[64:67], v[140:143], 0
	v_exp_f32_e32 v225, v225
	v_exp_f32_e32 v226, v226
	v_exp_f32_e32 v162, v162
	v_exp_f32_e32 v163, v163
	v_exp_f32_e32 v234, v167
	v_exp_f32_e32 v235, v222
	v_exp_f32_e32 v161, v161
	s_waitcnt lgkmcnt(2)
	v_mfma_f32_32x32x16_bf16 v[64:79], v[68:71], v[140:143], 0
	v_exp_f32_e32 v240, v238
	v_exp_f32_e32 v239, v239
	v_exp_f32_e32 v160, v160
	s_waitcnt lgkmcnt(0)
	v_mfma_f32_32x32x16_bf16 v[64:79], v[230:233], v[136:139], v[64:79]
	v_mfma_f32_32x32x16_bf16 v[80:95], v[214:217], v[136:139], v[80:95]
	ds_read_b128 v[214:217], v196 offset:32768
	ds_read_b128 v[230:233], v196 offset:45056
	s_waitcnt lgkmcnt(0)
	v_mfma_f32_32x32x16_bf16 v[64:79], v[230:233], v[132:135], v[64:79]
	v_mfma_f32_32x32x16_bf16 v[80:95], v[214:217], v[132:135], v[80:95]
	ds_read_b128 v[214:217], v195 offset:32768
	ds_read_b128 v[230:233], v195 offset:45056
	s_waitcnt lgkmcnt(0)
	v_mfma_f32_32x32x16_bf16 v[64:79], v[230:233], v[128:131], v[64:79]
	v_mfma_f32_32x32x16_bf16 v[80:95], v[214:217], v[128:131], v[80:95]
	ds_read_b128 v[214:217], v193 offset:32768
	ds_read_b128 v[230:233], v193 offset:45056
	s_waitcnt lgkmcnt(0)
	v_mfma_f32_32x32x16_bf16 v[64:79], v[230:233], v[124:127], v[64:79]
	v_mfma_f32_32x32x16_bf16 v[80:95], v[214:217], v[124:127], v[80:95]
	ds_read_b128 v[214:217], v192 offset:32768
	ds_read_b128 v[230:233], v192 offset:45056
	s_waitcnt lgkmcnt(0)
	v_mfma_f32_32x32x16_bf16 v[64:79], v[230:233], v[120:123], v[64:79]
	v_mfma_f32_32x32x16_bf16 v[80:95], v[214:217], v[120:123], v[80:95]
	ds_read_b128 v[214:217], v186 offset:32768
	ds_read_b128 v[230:233], v186 offset:45056
	s_waitcnt lgkmcnt(0)
	v_mfma_f32_32x32x16_bf16 v[64:79], v[230:233], v[116:119], v[64:79]
	v_mfma_f32_32x32x16_bf16 v[80:95], v[214:217], v[116:119], v[80:95]
	ds_read_b128 v[214:217], v189 offset:32768
	ds_read_b128 v[230:233], v189 offset:45056
	s_waitcnt lgkmcnt(0)
	v_mfma_f32_32x32x16_bf16 v[64:79], v[230:233], v[112:115], v[64:79]
	v_mfma_f32_32x32x16_bf16 v[80:95], v[214:217], v[112:115], v[80:95]
	ds_read_b128 v[214:217], v190 offset:32768
	ds_read_b128 v[230:233], v190 offset:45056
	s_waitcnt lgkmcnt(0)
	v_mfma_f32_32x32x16_bf16 v[64:79], v[230:233], v[108:111], v[64:79]
	v_mfma_f32_32x32x16_bf16 v[80:95], v[214:217], v[108:111], v[80:95]
	ds_read_b128 v[214:217], v188 offset:32768
	ds_read_b128 v[230:233], v188 offset:45056
	s_waitcnt lgkmcnt(0)
	v_mfma_f32_32x32x16_bf16 v[64:79], v[230:233], v[104:107], v[64:79]
	v_mfma_f32_32x32x16_bf16 v[80:95], v[214:217], v[104:107], v[80:95]
	ds_read_b128 v[214:217], v199 offset:32768
	ds_read_b128 v[230:233], v199 offset:45056
	s_waitcnt lgkmcnt(0)
	v_mfma_f32_32x32x16_bf16 v[64:79], v[230:233], v[100:103], v[64:79]
	v_mfma_f32_32x32x16_bf16 v[80:95], v[214:217], v[100:103], v[80:95]
	ds_read_b128 v[214:217], v198 offset:32768
	ds_read_b128 v[230:233], v198 offset:45056
	s_waitcnt lgkmcnt(0)
	v_mfma_f32_32x32x16_bf16 v[64:79], v[230:233], v[96:99], v[64:79]
	v_exp_f32_e32 v231, v164
	v_add_f32_e32 v164, 0, v157
	v_add_f32_e32 v164, v159, v164
	v_add_f32_e32 v164, v155, v164
	v_add_f32_e32 v164, v158, v164
	v_add_f32_e32 v164, v154, v164
	v_add_f32_e32 v164, v156, v164
	v_add_f32_e32 v164, v152, v164
	v_add_f32_e32 v164, v153, v164
	v_add_f32_e32 v164, v149, v164
	v_add_f32_e32 v164, v151, v164
	v_add_f32_e32 v164, v148, v164
	v_add_f32_e32 v164, v150, v164
	v_add_f32_e32 v164, v145, v164
	v_add_f32_e32 v164, v147, v164
	v_add_f32_e32 v164, v144, v164
	v_add_f32_e32 v164, v146, v164
	v_exp_f32_e32 v230, v227
	v_add_f32_e32 v164, v223, v164
	v_add_f32_e32 v164, v224, v164
	v_add_f32_e32 v164, v225, v164
	v_add_f32_e32 v164, v226, v164
	v_exp_f32_e32 v232, v165
	v_add_f32_e32 v164, v230, v164
	v_exp_f32_e32 v233, v166
	v_add_f32_e32 v164, v162, v164
	v_add_f32_e32 v164, v163, v164
	v_add_f32_e32 v164, v231, v164
	v_add_f32_e32 v164, v232, v164
	v_add_f32_e32 v164, v233, v164
	v_mfma_f32_32x32x16_bf16 v[80:95], v[214:217], v[96:99], v[80:95]
	v_add_f32_e32 v164, v234, v164
	v_add_f32_e32 v164, v235, v164
	v_add_f32_e32 v164, v161, v164
	v_add_f32_e32 v164, v240, v164
	v_add_f32_e32 v164, v239, v164
	v_add_f32_e32 v227, v160, v164
	v_mov_b32_e32 v238, v227
	v_cvt_pk_bf16_f32 v164, v157, v159
	v_cvt_pk_bf16_f32 v165, v155, v158
	v_cvt_pk_bf16_f32 v166, v154, v156
	v_cvt_pk_bf16_f32 v167, v152, v153
	s_nop 1
	v_permlane32_swap_b32_e32 v227, v238
	v_permlane32_swap_b32_e32 v164, v166
	v_permlane32_swap_b32_e32 v165, v167
	v_cvt_pk_bf16_f32 v214, v149, v151
	v_cvt_pk_bf16_f32 v215, v148, v150
	v_cvt_pk_bf16_f32 v216, v145, v147
	v_cvt_pk_bf16_f32 v217, v144, v146
	v_cvt_pk_bf16_f32 v222, v223, v224
	v_cvt_pk_bf16_f32 v223, v225, v226
	v_cvt_pk_bf16_f32 v224, v230, v162
	v_cvt_pk_bf16_f32 v225, v163, v231
	v_cvt_pk_bf16_f32 v230, v232, v233
	v_cvt_pk_bf16_f32 v231, v234, v235
	v_cvt_pk_bf16_f32 v232, v161, v240
	v_cvt_pk_bf16_f32 v233, v239, v160
	s_nop 0
	v_permlane32_swap_b32_e32 v214, v216
	v_permlane32_swap_b32_e32 v215, v217
	v_permlane32_swap_b32_e32 v222, v224
	v_permlane32_swap_b32_e32 v223, v225
	v_permlane32_swap_b32_e32 v230, v232
	v_permlane32_swap_b32_e32 v231, v233
	s_mov_b32 s2, 0x4bfc0000
	v_add_co_u32_e32 v148, vcc, s2, v172
	s_mov_b32 s2, 0x4bfe0000
	s_nop 0
	v_addc_co_u32_e32 v149, vcc, 0, v173, vcc
	v_add_co_u32_e32 v152, vcc, s2, v172
	s_mov_b32 s2, 0x45406000
	s_nop 0
	v_addc_co_u32_e32 v153, vcc, 0, v173, vcc
	global_load_dwordx4 v[144:147], v[148:149], off offset:256
	s_nop 0
	global_load_dwordx4 v[148:151], v[148:149], off
	s_nop 0
	global_load_dwordx4 v[156:159], v[152:153], off offset:256
	s_nop 0
	global_load_dwordx4 v[152:155], v[152:153], off
	v_add_co_u32_e32 v160, vcc, s2, v174
	s_nop 1
	v_addc_co_u32_e32 v161, vcc, 0, v175, vcc
	global_load_dwordx4 v[160:163], v[160:161], off
	ds_read_b64_tr_b16 v[172:173], v181 offset:0
	ds_read_b64_tr_b16 v[174:175], v181 offset:0x800
	ds_read_b64_tr_b16 v[240:241], v181 offset:0x200
	ds_read_b64_tr_b16 v[242:243], v181 offset:0xa00
	ds_read_b64_tr_b16 v[244:245], v181 offset:0x400
	ds_read_b64_tr_b16 v[246:247], v181 offset:0xc00
	ds_read_b64_tr_b16 v[248:249], v181 offset:0x600
	ds_read_b64_tr_b16 v[250:251], v181 offset:0xe00
	s_waitcnt lgkmcnt(6)
	s_nop 0
	v_mfma_f32_32x32x16_bf16 v[0:15], v[164:167], v[172:175], v[0:15]
	ds_read_b64_tr_b16 v[172:173], v181 offset:0x1000
	ds_read_b64_tr_b16 v[174:175], v181 offset:0x1800
	s_waitcnt lgkmcnt(6)
	v_mfma_f32_32x32x16_bf16 v[48:63], v[164:167], v[240:243], v[48:63]
	ds_read_b64_tr_b16 v[240:241], v181 offset:0x1200
	ds_read_b64_tr_b16 v[242:243], v181 offset:0x1a00
	s_waitcnt lgkmcnt(6)
	v_mfma_f32_32x32x16_bf16 v[32:47], v[164:167], v[244:247], v[32:47]
	ds_read_b64_tr_b16 v[244:245], v181 offset:0x1400
	ds_read_b64_tr_b16 v[246:247], v181 offset:0x1c00
	s_waitcnt lgkmcnt(6)
	v_mfma_f32_32x32x16_bf16 v[16:31], v[164:167], v[248:251], v[16:31]
	ds_read_b64_tr_b16 v[248:249], v181 offset:0x1600
	ds_read_b64_tr_b16 v[250:251], v181 offset:0x1e00
	s_waitcnt lgkmcnt(6)
	v_mfma_f32_32x32x16_bf16 v[0:15], v[214:217], v[172:175], v[0:15]
	ds_read_b64_tr_b16 v[172:173], v181 offset:0x2000
	ds_read_b64_tr_b16 v[174:175], v181 offset:0x2800
	v_max_f32_e32 v164, v81, v81
	v_max_f32_e32 v165, v80, v80
	v_max_f32_e32 v164, v165, v164
	v_max3_f32 v164, v164, v82, v83
	v_max3_f32 v164, v164, v84, v85
	v_max3_f32 v164, v164, v86, v87
	v_max3_f32 v164, v164, v88, v89
	v_max3_f32 v164, v164, v90, v91
	s_waitcnt lgkmcnt(6)
	v_mfma_f32_32x32x16_bf16 v[48:63], v[214:217], v[240:243], v[48:63]
	ds_read_b64_tr_b16 v[240:241], v181 offset:0x2200
	ds_read_b64_tr_b16 v[242:243], v181 offset:0x2a00
	s_waitcnt lgkmcnt(6)
	v_mfma_f32_32x32x16_bf16 v[32:47], v[214:217], v[244:247], v[32:47]
	ds_read_b64_tr_b16 v[244:245], v181 offset:0x2400
	ds_read_b64_tr_b16 v[246:247], v181 offset:0x2c00
	v_max3_f32 v164, v164, v92, v93
	v_max3_f32 v164, v164, v94, v95
	v_max3_f32 v164, v164, v64, v65
	v_max3_f32 v164, v164, v66, v67
	v_max3_f32 v164, v164, v68, v69
	v_max3_f32 v164, v164, v70, v71
	v_max3_f32 v164, v164, v72, v73
	v_max3_f32 v164, v164, v74, v75
	s_waitcnt lgkmcnt(6)
	v_mfma_f32_32x32x16_bf16 v[16:31], v[214:217], v[248:251], v[16:31]
	ds_read_b64_tr_b16 v[248:249], v181 offset:0x2600
	ds_read_b64_tr_b16 v[250:251], v181 offset:0x2e00
	s_waitcnt lgkmcnt(6)
	v_mfma_f32_32x32x16_bf16 v[0:15], v[222:225], v[172:175], v[0:15]
	ds_read_b64_tr_b16 v[172:173], v181 offset:0x3000
	ds_read_b64_tr_b16 v[174:175], v181 offset:0x3800
	v_max3_f32 v164, v164, v76, v77
	v_max3_f32 v164, v164, v78, v79
	v_mov_b32_e32 v165, v164
	s_nop 1
	v_permlane32_swap_b32_e32 v164, v165
	v_max_f32_e32 v165, v165, v165
	v_max_f32_e32 v164, v164, v164
	v_max_f32_e32 v164, v164, v165
	s_waitcnt lgkmcnt(6)
	v_mfma_f32_32x32x16_bf16 v[48:63], v[222:225], v[240:243], v[48:63]
	ds_read_b64_tr_b16 v[240:241], v181 offset:0x3200
	ds_read_b64_tr_b16 v[242:243], v181 offset:0x3a00
	s_waitcnt lgkmcnt(6)
	v_mfma_f32_32x32x16_bf16 v[32:47], v[222:225], v[244:247], v[32:47]
	ds_read_b64_tr_b16 v[244:245], v181 offset:0x3400
	ds_read_b64_tr_b16 v[246:247], v181 offset:0x3c00
	v_sub_f32_e32 v165, v164, v207
	v_cmp_ge_f32_e32 vcc, s46, v165
	v_max_f32_e32 v165, v207, v207
	v_max_f32_e32 v165, v165, v164
	v_sub_f32_e32 v164, v207, v165
	v_mul_f32_e32 v164, 0x3dd53b94, v164
	v_exp_f32_e32 v164, v164
	s_cmp_eq_u64 vcc, exec
	s_cselect_b64 s[38:39], -1, 0
	s_waitcnt lgkmcnt(6)
	v_mfma_f32_32x32x16_bf16 v[16:31], v[222:225], v[248:251], v[16:31]
	ds_read_b64_tr_b16 v[248:249], v181 offset:0x3600
	ds_read_b64_tr_b16 v[250:251], v181 offset:0x3e00
	v_cndmask_b32_e64 v166, v165, v207, s[38:39]
	v_mul_f32_e32 v167, 0xbdd53b94, v166
	v_fmamk_f32 v80, v80, 0x3dd53b94, v167
	v_fmamk_f32 v81, v81, 0x3dd53b94, v167
	v_fmamk_f32 v82, v82, 0x3dd53b94, v167
	v_fmamk_f32 v83, v83, 0x3dd53b94, v167
	v_fmamk_f32 v84, v84, 0x3dd53b94, v167
	v_fmamk_f32 v85, v85, 0x3dd53b94, v167
	v_fmamk_f32 v86, v86, 0x3dd53b94, v167
	v_fmamk_f32 v87, v87, 0x3dd53b94, v167
	s_waitcnt lgkmcnt(6)
	v_mfma_f32_32x32x16_bf16 v[0:15], v[230:233], v[172:175], v[0:15]
	v_fmamk_f32 v88, v88, 0x3dd53b94, v167
	v_fmamk_f32 v89, v89, 0x3dd53b94, v167
	v_fmamk_f32 v90, v90, 0x3dd53b94, v167
	v_fmamk_f32 v91, v91, 0x3dd53b94, v167
	v_fmamk_f32 v92, v92, 0x3dd53b94, v167
	v_fmamk_f32 v93, v93, 0x3dd53b94, v167
	v_fmamk_f32 v94, v94, 0x3dd53b94, v167
	s_waitcnt lgkmcnt(0)
	s_barrier
	v_mfma_f32_32x32x16_bf16 v[48:63], v[230:233], v[240:243], v[48:63]
	s_waitcnt vmcnt(0)
	v_cndmask_b32_e64 v164, v164, 1.0, s[38:39]
	v_cmp_gt_f32_e32 vcc, 1.0, v164
	s_waitcnt vmcnt(4)
	ds_write_b128 v183, v[144:147] offset:16384
	s_waitcnt vmcnt(2)
	ds_write_b128 v184, v[156:159] offset:16384
	v_mfma_f32_32x32x16_bf16 v[32:47], v[230:233], v[244:247], v[32:47]
	ds_write_b128 v185, v[148:151] offset:57344
	s_waitcnt vmcnt(1)
	ds_write_b128 v187, v[152:155] offset:57344
	s_waitcnt vmcnt(0)
	ds_write_b128 v191, v[160:163] offset:57344
	v_mfma_f32_32x32x16_bf16 v[16:31], v[230:233], v[248:251], v[16:31]
	s_cbranch_vccz .LBB0_1143
	s_and_saveexec_b64 s[2:3], s[36:37]
	ds_write_b32 v179, v164 offset:128
	s_or_b64 exec, exec, s[2:3]
	s_waitcnt lgkmcnt(0)
	v_add_u32_e32 v156, s14, v178
	ds_read_b128 v[144:147], v156 offset:224
	ds_read_b128 v[148:151], v156 offset:192
	ds_read_b128 v[152:155], v156 offset:160
	ds_read_b128 v[156:159], v156 offset:128
	s_waitcnt lgkmcnt(3)
	v_pk_mul_f32 v[12:13], v[12:13], v[144:145]
	s_waitcnt lgkmcnt(2)
	v_pk_mul_f32 v[8:9], v[8:9], v[148:149]
	s_waitcnt lgkmcnt(1)
	v_pk_mul_f32 v[4:5], v[4:5], v[152:153]
	v_pk_mul_f32 v[14:15], v[14:15], v[146:147]
	v_pk_mul_f32 v[10:11], v[10:11], v[150:151]
	v_pk_mul_f32 v[6:7], v[6:7], v[154:155]
	s_waitcnt lgkmcnt(0)
	v_pk_mul_f32 v[2:3], v[2:3], v[158:159]
	v_pk_mul_f32 v[0:1], v[0:1], v[156:157]
	v_pk_mul_f32 v[60:61], v[60:61], v[144:145]
	v_pk_mul_f32 v[56:57], v[56:57], v[148:149]
	v_pk_mul_f32 v[52:53], v[52:53], v[152:153]
	v_pk_mul_f32 v[62:63], v[62:63], v[146:147]
	v_pk_mul_f32 v[58:59], v[58:59], v[150:151]
	v_pk_mul_f32 v[54:55], v[54:55], v[154:155]
	v_pk_mul_f32 v[50:51], v[50:51], v[158:159]
	v_pk_mul_f32 v[48:49], v[48:49], v[156:157]
	v_pk_mul_f32 v[44:45], v[44:45], v[144:145]
	v_pk_mul_f32 v[40:41], v[40:41], v[148:149]
	v_pk_mul_f32 v[36:37], v[36:37], v[152:153]
	v_pk_mul_f32 v[46:47], v[46:47], v[146:147]
	v_pk_mul_f32 v[42:43], v[42:43], v[150:151]
	v_pk_mul_f32 v[38:39], v[38:39], v[154:155]
	v_pk_mul_f32 v[34:35], v[34:35], v[158:159]
	v_pk_mul_f32 v[32:33], v[32:33], v[156:157]
	v_pk_mul_f32 v[28:29], v[28:29], v[144:145]
	v_pk_mul_f32 v[24:25], v[24:25], v[148:149]
	v_pk_mul_f32 v[20:21], v[20:21], v[152:153]
	v_pk_mul_f32 v[30:31], v[30:31], v[146:147]
	v_pk_mul_f32 v[26:27], v[26:27], v[150:151]
	v_pk_mul_f32 v[22:23], v[22:23], v[154:155]
	v_pk_mul_f32 v[18:19], v[18:19], v[158:159]
	v_pk_mul_f32 v[16:17], v[16:17], v[156:157]
.LBB0_1143:
	v_cndmask_b32_e64 v207, v165, v207, s[38:39]
	v_mul_f32_e32 v144, 0xbdd53b94, v207
	v_mov_b32_e32 v145, v144
	v_fmac_f32_e32 v145, 0x3dd53b94, v95
	v_exp_f32_e32 v165, v80
	v_exp_f32_e32 v224, v81
	v_exp_f32_e32 v166, v82
	v_exp_f32_e32 v225, v83
	v_exp_f32_e32 v223, v84
	v_exp_f32_e32 v226, v85
	v_exp_f32_e32 v167, v86
	v_exp_f32_e32 v222, v87
	v_exp_f32_e32 v172, v88
	v_exp_f32_e32 v174, v89
	v_exp_f32_e32 v173, v90
	v_exp_f32_e32 v175, v91
	v_exp_f32_e32 v160, v92
	v_exp_f32_e32 v162, v93
	v_exp_f32_e32 v161, v94
	v_exp_f32_e32 v163, v145
	v_pk_fma_f32 v[158:159], v[64:65], s[96:97], v[144:145] op_sel_hi:[1,0,0]
	v_add_f32_e32 v64, v219, v220
	v_fmac_f32_e32 v64, v218, v180
	v_add_f32_e32 v180, v227, v238
	s_mov_b64 s[2:3], 0x4000
	s_add_i32 s15, s15, 2
	v_pk_fma_f32 v[156:157], v[66:67], s[96:97], v[144:145] op_sel_hi:[1,0,0]
	v_pk_fma_f32 v[152:153], v[68:69], s[96:97], v[144:145] op_sel_hi:[1,0,0]
	v_pk_fma_f32 v[148:149], v[70:71], s[96:97], v[144:145] op_sel_hi:[1,0,0]
	v_pk_fma_f32 v[146:147], v[72:73], s[96:97], v[144:145] op_sel_hi:[1,0,0]
	v_pk_fma_f32 v[154:155], v[74:75], s[96:97], v[144:145] op_sel_hi:[1,0,0]
	v_pk_fma_f32 v[150:151], v[76:77], s[96:97], v[144:145] op_sel_hi:[1,0,0]
	v_pk_fma_f32 v[144:145], v[78:79], s[96:97], v[144:145] op_sel_hi:[1,0,0]
	v_fmac_f32_e32 v180, v64, v221
	v_lshl_add_u64 v[168:169], v[168:169], 0, s[2:3]
	s_cmp_ge_i32 s15, s10
	v_lshl_add_u64 v[170:171], v[170:171], 0, s[58:59]
	s_waitcnt lgkmcnt(0)
	s_barrier
	s_cbranch_scc1 .LBB0_1145
	v_mov_b32_e32 v218, v164
	s_branch .LBB0_1135
